# v42: v26 with hipcc's f32->bf16 round-to-nearest-even bit trick (bfe/add3/shift/and_or on value pairs) replaced by v_cvt_pk_bf16_f32 in the RWKV prep (P5) and post (P7) loops
# speedup vs baseline: 1.0127x; 1.0013x over previous
.LBB0_934:
	s_or_b64 exec, exec, s[0:1]
	v_div_scale_f32 v88, s[0:1], v75, v75, 1.0
	v_rcp_f32_e32 v89, v88
	v_pk_mul_f32 v[58:59], v[58:59], v[86:87]
	v_pk_mul_f32 v[60:61], v[60:61], v[90:91]
	v_pk_mul_f32 v[18:19], v[18:19], v[74:75]
	v_fma_f32 v86, -v88, v89, 1.0
	v_fmac_f32_e32 v89, v86, v89
	v_div_scale_f32 v86, vcc, 1.0, v75, 1.0
	v_mul_f32_e32 v87, v86, v89
	v_fma_f32 v90, -v88, v87, v86
	v_fmac_f32_e32 v87, v90, v89
	v_fma_f32 v86, -v88, v87, v86
	v_div_scale_f32 v88, s[0:1], v74, v74, 1.0
	v_rcp_f32_e32 v90, v88
	v_div_fmas_f32 v86, v86, v89, v87
	v_div_fixup_f32 v75, v86, v75, 1.0
	v_pk_mul_f32 v[20:21], v[20:21], v[76:77]
	v_fma_f32 v86, -v88, v90, 1.0
	v_fmac_f32_e32 v90, v86, v90
	v_div_scale_f32 v86, vcc, 1.0, v74, 1.0
	v_mul_f32_e32 v87, v86, v90
	v_fma_f32 v89, -v88, v87, v86
	v_fmac_f32_e32 v87, v89, v90
	v_fma_f32 v86, -v88, v87, v86
	v_div_scale_f32 v88, s[0:1], v77, v77, 1.0
	v_rcp_f32_e32 v89, v88
	v_div_fmas_f32 v86, v86, v90, v87
	v_div_fixup_f32 v74, v86, v74, 1.0
	v_pk_mul_f32 v[164:165], v[46:47], v[74:75]
	v_fma_f32 v86, -v88, v89, 1.0
	v_fmac_f32_e32 v89, v86, v89
	v_div_scale_f32 v86, vcc, 1.0, v77, 1.0
	v_mul_f32_e32 v87, v86, v89
	v_fma_f32 v90, -v88, v87, v86
	v_fmac_f32_e32 v87, v90, v89
	v_fma_f32 v86, -v88, v87, v86
	v_div_scale_f32 v88, s[0:1], v76, v76, 1.0
	v_rcp_f32_e32 v90, v88
	v_div_fmas_f32 v86, v86, v89, v87
	v_div_fixup_f32 v77, v86, v77, 1.0
	s_nop 0
	v_fma_f32 v86, -v88, v90, 1.0
	v_fmac_f32_e32 v90, v86, v90
	v_div_scale_f32 v86, vcc, 1.0, v76, 1.0
	v_mul_f32_e32 v87, v86, v90
	s_nop 0
	s_nop 0
	v_fma_f32 v89, -v88, v87, v86
	s_nop 0
	s_nop 0
	v_fmac_f32_e32 v87, v89, v90
	v_cvt_pk_bf16_f32 v22, v22, v23
	s_nop 0
	v_fma_f32 v86, -v88, v87, v86
	s_nop 0
	s_nop 0
	v_div_fmas_f32 v86, v86, v90, v87
	s_nop 0
	s_nop 0
	v_div_fixup_f32 v76, v86, v76, 1.0
	v_cvt_pk_bf16_f32 v23, v24, v25
	v_lshl_add_u64 v[24:25], v[160:161], 0, v[184:185]
	s_mov_b64 s[0:1], 0x2900
	v_pk_mul_f32 v[210:211], v[52:53], v[76:77]
	v_pk_mul_f32 v[162:163], v[48:49], v[76:77]
	v_lshl_add_u64 v[48:49], v[24:25], 0, s[0:1]
	v_div_scale_f32 v52, s[0:1], v67, v67, 1.0
	v_rcp_f32_e32 v53, v52
	v_add_co_u32_e32 v24, vcc, s73, v24
	v_pk_mul_f32 v[212:213], v[50:51], v[74:75]
	s_nop 0
	v_addc_co_u32_e32 v25, vcc, 0, v25, vcc
	global_store_dwordx2 v[24:25], v[22:23], off offset:2304
	v_pk_mul_f32 v[24:25], v[54:55], v[66:67]
	v_fma_f32 v54, -v52, v53, 1.0
	v_fmac_f32_e32 v53, v54, v53
	v_div_scale_f32 v54, vcc, 1.0, v67, 1.0
	v_mul_f32_e32 v55, v54, v53
	v_pk_mul_f32 v[22:23], v[56:57], v[68:69]
	v_fma_f32 v56, -v52, v55, v54
	v_fmac_f32_e32 v55, v56, v53
	v_fma_f32 v52, -v52, v55, v54
	v_div_scale_f32 v54, s[0:1], v66, v66, 1.0
	v_rcp_f32_e32 v56, v54
	v_div_fmas_f32 v52, v52, v53, v55
	v_div_fixup_f32 v53, v52, v67, 1.0
	v_pk_mul_f32 v[50:51], v[110:111], v[82:83]
	v_fma_f32 v52, -v54, v56, 1.0
	v_fmac_f32_e32 v56, v52, v56
	v_div_scale_f32 v52, vcc, 1.0, v66, 1.0
	v_mul_f32_e32 v55, v52, v56
	v_fma_f32 v57, -v54, v55, v52
	v_fmac_f32_e32 v55, v57, v56
	v_fma_f32 v52, -v54, v55, v52
	v_div_scale_f32 v54, s[0:1], v69, v69, 1.0
	v_rcp_f32_e32 v57, v54
	v_div_fmas_f32 v52, v52, v56, v55
	v_div_fixup_f32 v52, v52, v66, 1.0
	v_pk_mul_f32 v[220:221], v[102:103], v[52:53]
	v_fma_f32 v55, -v54, v57, 1.0
	v_fmac_f32_e32 v57, v55, v57
	v_div_scale_f32 v55, vcc, 1.0, v69, 1.0
	v_mul_f32_e32 v56, v55, v57
	v_fma_f32 v66, -v54, v56, v55
	v_fmac_f32_e32 v56, v66, v57
	v_div_scale_f32 v66, s[0:1], v68, v68, 1.0
	v_rcp_f32_e32 v67, v66
	v_fma_f32 v54, -v54, v56, v55
	v_div_fmas_f32 v54, v54, v57, v56
	v_div_fixup_f32 v55, v54, v69, 1.0
	v_fma_f32 v54, -v66, v67, 1.0
	v_fmac_f32_e32 v67, v54, v67
	v_div_scale_f32 v54, vcc, 1.0, v68, 1.0
	v_mul_f32_e32 v56, v54, v67
	v_fma_f32 v57, -v66, v56, v54
	v_fmac_f32_e32 v56, v57, v67
	v_fma_f32 v54, -v66, v56, v54
	v_div_fmas_f32 v54, v54, v67, v56
	v_div_scale_f32 v56, s[0:1], v63, v63, 1.0
	v_rcp_f32_e32 v57, v56
	v_div_fixup_f32 v54, v54, v68, 1.0
	v_pk_mul_f32 v[168:169], v[98:99], v[52:53]
	s_nop 0
	v_fma_f32 v66, -v56, v57, 1.0
	v_fmac_f32_e32 v57, v66, v57
	v_div_scale_f32 v66, vcc, 1.0, v63, 1.0
	v_mul_f32_e32 v67, v66, v57
	v_fma_f32 v68, -v56, v67, v66
	v_fmac_f32_e32 v67, v68, v57
	v_fma_f32 v56, -v56, v67, v66
	v_div_scale_f32 v66, s[0:1], v62, v62, 1.0
	v_rcp_f32_e32 v68, v66
	v_div_fmas_f32 v56, v56, v57, v67
	v_div_fixup_f32 v57, v56, v63, 1.0
	s_nop 0
	v_fma_f32 v56, -v66, v68, 1.0
	s_nop 0
	v_fmac_f32_e32 v68, v56, v68
	v_div_scale_f32 v56, vcc, 1.0, v62, 1.0
	s_nop 0
	v_pk_mul_f32 v[52:53], v[106:107], v[62:63]
	v_mul_f32_e32 v63, v56, v68
	v_fma_f32 v67, -v66, v63, v56
	v_fmac_f32_e32 v63, v67, v68
	v_fma_f32 v56, -v66, v63, v56
	v_div_scale_f32 v66, s[0:1], v65, v65, 1.0
	v_rcp_f32_e32 v67, v66
	v_div_fmas_f32 v56, v56, v68, v63
	v_div_fixup_f32 v56, v56, v62, 1.0
	s_nop 0
	v_fma_f32 v62, -v66, v67, 1.0
	v_fmac_f32_e32 v67, v62, v67
	v_div_scale_f32 v62, vcc, 1.0, v65, 1.0
	v_mul_f32_e32 v63, v62, v67
	v_fma_f32 v68, -v66, v63, v62
	v_fmac_f32_e32 v63, v68, v67
	v_fma_f32 v62, -v66, v63, v62
	v_div_scale_f32 v66, s[0:1], v64, v64, 1.0
	v_rcp_f32_e32 v68, v66
	v_cvt_pk_bf16_f32 v26, v26, v27
	s_nop 0
	v_div_fmas_f32 v62, v62, v67, v63
	s_nop 0
	s_nop 0
	v_div_fixup_f32 v63, v62, v65, 1.0
	v_fma_f32 v62, -v66, v68, 1.0
	s_nop 0
	s_nop 0
	v_fmac_f32_e32 v68, v62, v68
	v_div_scale_f32 v62, vcc, 1.0, v64, 1.0
	v_cvt_pk_bf16_f32 v27, v28, v29
	v_pk_mul_f32 v[28:29], v[108:109], v[64:65]
	v_mul_f32_e32 v65, v62, v68
	v_fma_f32 v67, -v66, v65, v62
	v_fmac_f32_e32 v65, v67, v68
	v_pk_mul_f32 v[228:229], v[134:135], v[56:57]
	v_pk_mul_f32 v[216:217], v[126:127], v[56:57]
	s_nop 0
	v_fma_f32 v62, -v66, v65, v62
	s_nop 0
	s_nop 0
	v_div_fmas_f32 v62, v62, v68, v65
	s_nop 0
	s_nop 0
	v_div_scale_f32 v66, s[0:1], v43, v43, 1.0
	v_div_fixup_f32 v62, v62, v64, 1.0
	v_cvt_pk_bf16_f32 v56, v94, v95
	s_nop 0
	v_rcp_f32_e32 v67, v66
	v_pk_mul_f32 v[226:227], v[136:137], v[62:63]
	v_pk_mul_f32 v[214:215], v[128:129], v[62:63]
	s_nop 0
	s_nop 0
	s_nop 0
	s_nop 0
	v_cvt_pk_bf16_f32 v57, v96, v97
	global_store_dwordx2 v[48:49], v[56:57], off offset:64
	v_pk_mul_f32 v[56:57], v[40:41], v[72:73]
	v_pk_mul_f32 v[40:41], v[38:39], v[70:71]
	v_fma_f32 v38, -v66, v67, 1.0
	v_fmac_f32_e32 v67, v38, v67
	v_div_scale_f32 v38, vcc, 1.0, v43, 1.0
	v_mul_f32_e32 v39, v38, v67
	v_fma_f32 v68, -v66, v39, v38
	v_fmac_f32_e32 v39, v68, v67
	v_fma_f32 v38, -v66, v39, v38
	v_div_scale_f32 v66, s[0:1], v42, v42, 1.0
	v_rcp_f32_e32 v68, v66
	v_div_fmas_f32 v38, v38, v67, v39
	v_div_fixup_f32 v39, v38, v43, 1.0
	v_pk_mul_f32 v[64:65], v[138:139], v[42:43]
	v_fma_f32 v38, -v66, v68, 1.0
	v_fmac_f32_e32 v68, v38, v68
	v_div_scale_f32 v38, vcc, 1.0, v42, 1.0
	v_mul_f32_e32 v43, v38, v68
	v_fma_f32 v67, -v66, v43, v38
	v_fmac_f32_e32 v43, v67, v68
	v_fma_f32 v38, -v66, v43, v38
	v_div_scale_f32 v66, s[0:1], v45, v45, 1.0
	v_rcp_f32_e32 v67, v66
	v_div_fmas_f32 v38, v38, v68, v43
	v_div_fixup_f32 v38, v38, v42, 1.0
	v_pk_mul_f32 v[62:63], v[140:141], v[44:45]
	v_fma_f32 v42, -v66, v67, 1.0
	v_fmac_f32_e32 v67, v42, v67
	v_div_scale_f32 v42, vcc, 1.0, v45, 1.0
	v_mul_f32_e32 v43, v42, v67
	v_fma_f32 v68, -v66, v43, v42
	v_fmac_f32_e32 v43, v68, v67
	v_fma_f32 v42, -v66, v43, v42
	v_div_scale_f32 v66, s[0:1], v44, v44, 1.0
	v_rcp_f32_e32 v68, v66
	v_div_fmas_f32 v42, v42, v67, v43
	v_div_fixup_f32 v43, v42, v45, 1.0
	v_pk_mul_f32 v[224:225], v[30:31], v[38:39]
	v_fma_f32 v42, -v66, v68, 1.0
	v_fmac_f32_e32 v68, v42, v68
	v_div_scale_f32 v42, vcc, 1.0, v44, 1.0
	v_mul_f32_e32 v45, v42, v68
	v_fma_f32 v67, -v66, v45, v42
	v_fmac_f32_e32 v45, v67, v68
	s_nop 0
	v_fma_f32 v42, -v66, v45, v42
	s_nop 0
	s_nop 0
	v_div_fmas_f32 v42, v42, v68, v45
	s_nop 0
	s_nop 0
	v_div_fixup_f32 v42, v42, v44, 1.0
	v_cvt_pk_bf16_f32 v30, v114, v115
	s_nop 0
	v_pk_mul_f32 v[222:223], v[32:33], v[42:43]
	s_nop 0
	s_nop 0
	s_nop 0
	s_nop 0
	v_cvt_pk_bf16_f32 v31, v116, v117
	v_pk_mul_f32 v[46:47], v[112:113], v[84:85]
	v_pk_mul_f32 v[218:219], v[104:105], v[54:55]
	global_store_dwordx2 v[48:49], v[26:27], off offset:32
	global_store_dwordx2 v[48:49], v[30:31], off offset:96
	v_cvt_pk_bf16_f32 v30, v58, v59
	v_cvt_pk_bf16_f32 v31, v60, v61
	v_cvt_pk_bf16_f32 v32, v50, v51
	v_cvt_pk_bf16_f32 v33, v46, v47
	v_cvt_pk_bf16_f32 v18, v18, v19
	v_cvt_pk_bf16_f32 v19, v20, v21
	v_cvt_pk_bf16_f32 v20, v24, v25
	v_cvt_pk_bf16_f32 v21, v22, v23
	v_cvt_pk_bf16_f32 v22, v212, v213
	v_cvt_pk_bf16_f32 v23, v210, v211
	v_cvt_pk_bf16_f32 v24, v220, v221
	v_cvt_pk_bf16_f32 v25, v218, v219
	v_lshl_add_u64 v[50:51], v[160:161], 0, v[186:187]
	v_pk_mul_f32 v[166:167], v[100:101], v[54:55]
	v_pk_mul_f32 v[230:231], v[36:37], v[42:43]
	v_pk_mul_f32 v[232:233], v[34:35], v[38:39]
	v_cvt_pk_bf16_f32 v34, v164, v165
	v_cvt_pk_bf16_f32 v35, v162, v163
	v_cvt_pk_bf16_f32 v36, v168, v169
	v_cvt_pk_bf16_f32 v37, v166, v167
	global_store_dwordx4 v[50:51], v[30:33], off
	global_store_dwordx4 v[50:51], v[18:21], off offset:2048
	v_mfma_f32_16x16x32_bf16 v[42:45], v[22:25], v[30:33], 0
	v_mul_f32_e64 v26, v144, v80
	v_mul_f32_e64 v27, v145, v81
	v_pk_mul_f32 v[54:55], v[142:143], v[78:79]
	v_mov_b32_e32 v174, v183
	v_mfma_f32_16x16x32_bf16 v[22:25], v[22:25], v[18:21], 0
	v_cvt_pk_bf16_f32 v38, v54, v55
	v_cvt_pk_bf16_f32 v39, v26, v27
	v_cvt_pk_bf16_f32 v40, v40, v41
	v_mfma_f32_16x16x32_bf16 v[18:21], v[34:37], v[18:21], 0
	v_cvt_pk_bf16_f32 v41, v56, v57
	v_cvt_pk_bf16_f32 v26, v52, v53
	v_cvt_pk_bf16_f32 v27, v28, v29
	v_mfma_f32_16x16x32_bf16 v[30:33], v[34:37], v[30:33], 0
	v_cvt_pk_bf16_f32 v28, v64, v65
	v_cvt_pk_bf16_f32 v29, v62, v63
	v_cvt_pk_bf16_f32 v46, v228, v229
	v_cvt_pk_bf16_f32 v47, v226, v227
	v_cvt_pk_bf16_f32 v48, v232, v233
	v_cvt_pk_bf16_f32 v49, v230, v231
	v_cvt_pk_bf16_f32 v34, v216, v217
	v_cvt_pk_bf16_f32 v35, v214, v215
	v_cvt_pk_bf16_f32 v36, v224, v225
	v_cvt_pk_bf16_f32 v37, v222, v223
	global_store_dwordx4 v[50:51], v[38:41], off offset:1024
	global_store_dwordx4 v[50:51], v[26:29], off offset:3072
	v_mfma_f32_16x16x32_bf16 v[18:21], v[34:37], v[26:29], v[18:21]
	v_mfma_f32_16x16x32_bf16 v[22:25], v[46:49], v[26:29], v[22:25]
	v_mov_b32_e32 v27, v176
	v_mov_b32_e32 v28, s30
	v_mov_b32_e32 v26, s30
	v_mfma_f32_16x16x32_bf16 v[30:33], v[34:37], v[38:41], v[30:33]
	v_mov_b32_e32 v34, v183
	s_nop 0
	v_cmp_gt_i32_e32 vcc, v27, v34
	v_add_u32_e32 v29, 1, v27
	v_cmp_lt_i32_e64 s[0:1], v27, v34
	v_cndmask_b32_e32 v28, v18, v28, vcc
	v_cndmask_b32_e32 v26, v22, v26, vcc
	v_cmp_lt_i32_e32 vcc, v29, v34
	v_cndmask_b32_e64 v35, v28, v18, s[0:1]
	v_add_u32_e32 v18, 2, v27
	v_cndmask_b32_e64 v22, v26, v22, s[0:1]
	s_or_b64 s[16:17], vcc, s[0:1]
	v_cndmask_b32_e64 v23, 0, v23, s[0:1]
	v_cndmask_b32_e64 v36, 0, v19, s[0:1]
	v_cmp_lt_i32_e64 s[0:1], v18, v34
	v_mfma_f32_16x16x32_bf16 v[42:45], v[46:49], v[38:41], v[42:45]
	s_or_b64 s[18:19], s[0:1], s[16:17]
	v_cmp_gt_i32_e64 s[16:17], v18, v34
	v_add_u32_e32 v18, 3, v27
	s_nop 0
	v_cndmask_b32_e64 v24, v24, 0, s[16:17]
	v_cndmask_b32_e64 v37, v20, 0, s[16:17]
	v_cmp_lt_i32_e64 s[16:17], v18, v34
	s_or_b64 s[0:1], s[16:17], s[0:1]
	s_or_b64 s[18:19], s[16:17], s[18:19]
	s_or_b64 vcc, s[0:1], vcc
	v_cndmask_b32_e64 v30, 0, v30, s[18:19]
	v_cndmask_b32_e32 v27, 0, v43, vcc
	v_cndmask_b32_e32 v31, 0, v31, vcc
	v_cmp_gt_i32_e32 vcc, v18, v34
	s_nop 0
	v_cndmask_b32_e64 v20, 0, v32, s[0:1]
	v_cndmask_b32_e64 v32, v21, 0, vcc
	s_nop 0
	s_nop 0
	s_nop 0
	s_nop 0
	v_cndmask_b32_e64 v19, 0, v33, s[16:17]
	v_cvt_pk_bf16_f32 v18, v30, v31
	s_nop 0
	s_nop 0
	s_nop 0
	s_nop 0
	s_nop 0
	v_cvt_pk_bf16_f32 v19, v20, v19
	v_lshl_add_u64 v[20:21], v[160:161], 0, v[188:189]
	v_cndmask_b32_e64 v25, v25, 0, vcc
	v_add_co_u32_e32 v234, vcc, s73, v20
	s_nop 0
	s_nop 0
	v_addc_co_u32_e32 v235, vcc, 0, v21, vcc
	global_store_dwordx2 v[234:235], v[18:19], off offset:512
	s_nop 0
	s_nop 0
	s_nop 0
	s_nop 0
	s_nop 0
	v_cvt_pk_bf16_f32 v18, v22, v23
	s_nop 0
	s_nop 0
	s_nop 0
	s_nop 0
	v_cvt_pk_bf16_f32 v19, v24, v25
	global_store_dwordx2 v[234:235], v[18:19], off offset:1024
	s_nop 0
	s_nop 0
	s_nop 0
	s_nop 0
	s_nop 0
	v_cvt_pk_bf16_f32 v18, v35, v36
	s_nop 0
	s_nop 0
	s_nop 0
	s_nop 0
	s_nop 0
	v_cndmask_b32_e64 v29, 0, v45, s[16:17]
	v_cndmask_b32_e64 v28, 0, v44, s[0:1]
	v_cndmask_b32_e64 v26, 0, v42, s[18:19]
	v_cvt_pk_bf16_f32 v19, v37, v32
	global_store_dwordx2 v[234:235], v[18:19], off offset:1536
	ds_write_b128 v242, v[26:29] offset:37504
	s_waitcnt lgkmcnt(0)
	v_mov_b32_e32 v26, s31
	ds_read_b128 v[154:157], v26 offset:37568
	ds_read_b128 v[150:153], v26 offset:37632
	ds_read_b128 v[146:149], v26 offset:37696
	ds_read_b128 v[142:145], v26 offset:37760
	ds_read_b128 v[134:137], v26 offset:37824
	ds_read_b128 v[130:133], v26 offset:37840
	ds_read_b128 v[126:129], v26 offset:37888
	ds_read_b128 v[122:125], v26 offset:37904
	ds_read_b128 v[118:121], v26 offset:37952
	ds_read_b128 v[114:117], v26 offset:37968
	ds_read_b128 v[110:113], v26 offset:38016
	ds_read_b128 v[106:109], v26 offset:38032
	ds_read_b128 v[102:105], v26 offset:38080
	ds_read_b128 v[98:101], v26 offset:38096
	ds_read_b128 v[94:97], v26 offset:38112
	ds_read_b128 v[90:93], v26 offset:38144
	ds_read_b128 v[86:89], v26 offset:38160
	ds_read_b128 v[82:85], v26 offset:38176
	ds_read_b128 v[74:77], v26 offset:38208
	ds_read_b128 v[70:73], v26 offset:38224
	ds_read_b128 v[66:69], v26 offset:38240
	ds_read_b128 v[62:65], v26 offset:38272
	ds_read_b128 v[58:61], v26 offset:38288
	ds_read_b128 v[54:57], v26 offset:38304
	ds_read_b128 v[50:53], v26 offset:38336
	ds_read_b128 v[46:49], v26 offset:38352
	ds_read_b128 v[42:45], v26 offset:38368
	ds_read_b128 v[38:41], v26 offset:38384
	ds_read_b128 v[34:37], v26 offset:38400
	ds_read_b128 v[30:33], v26 offset:38416
	ds_read_b128 v[22:25], v26 offset:38432
	ds_read_b128 v[18:21], v26 offset:38448
	s_waitcnt lgkmcnt(14)
	ds_read_b128 v[156:159], v26 offset:38464
	ds_read_b128 v[138:141], v26 offset:38480
	ds_read_b128 v[78:81], v26 offset:38496
	ds_read_b128 v[26:29], v26 offset:38512
	s_and_saveexec_b64 s[0:1], s[10:11]
	s_cbranch_execz .LBB0_936
	v_cmp_eq_u32_e32 vcc, 15, v174
	s_waitcnt lgkmcnt(4)
	s_nop 0
	v_cndmask_b32_e64 v20, 0, 1.0, vcc
	v_cmp_eq_u32_e32 vcc, 0, v174
	s_nop 1
	v_cndmask_b32_e64 v21, 0, 1.0, vcc
	v_cmp_eq_u32_e32 vcc, 1, v174
	s_waitcnt lgkmcnt(3)
	v_fmac_f32_e32 v20, v21, v156
	s_waitcnt lgkmcnt(0)
	v_cndmask_b32_e64 v29, 0, 1.0, vcc
	v_cmp_eq_u32_e32 vcc, 2, v174
	v_fmac_f32_e32 v29, v21, v154
	v_fmac_f32_e32 v20, v29, v157
	v_cndmask_b32_e64 v39, 0, 1.0, vcc
	v_cmp_eq_u32_e32 vcc, 3, v174
	v_fmac_f32_e32 v39, v21, v150
	v_fmac_f32_e32 v39, v151, v29
	v_cndmask_b32_e64 v40, 0, 1.0, vcc
	v_cmp_eq_u32_e32 vcc, 4, v174
	v_fmac_f32_e32 v40, v21, v146
	v_fmac_f32_e32 v40, v29, v147
	v_cndmask_b32_e64 v41, 0, 1.0, vcc
	v_cmp_eq_u32_e32 vcc, 5, v174
	v_fmac_f32_e32 v41, v21, v142
	v_fmac_f32_e32 v41, v29, v143
	v_cndmask_b32_e64 v69, 0, 1.0, vcc
	v_cmp_eq_u32_e32 vcc, 6, v174
	v_fmac_f32_e32 v69, v21, v134
	v_fmac_f32_e32 v69, v29, v135
	v_cndmask_b32_e64 v84, 0, 1.0, vcc
	v_cmp_eq_u32_e32 vcc, 7, v174
	v_fmac_f32_e32 v84, v21, v126
	v_fmac_f32_e32 v84, v29, v127
	v_cndmask_b32_e64 v85, 0, 1.0, vcc
	v_cmp_eq_u32_e32 vcc, 8, v174
	v_fmac_f32_e32 v85, v21, v118
	v_fmac_f32_e32 v85, v29, v119
	v_cndmask_b32_e64 v95, 0, 1.0, vcc
	v_fmac_f32_e32 v95, v21, v110
	v_fmac_f32_e32 v95, v29, v111
	v_fmac_f32_e32 v20, v39, v158
	v_fmac_f32_e32 v40, v148, v39
	v_fmac_f32_e32 v41, v39, v144
	v_fmac_f32_e32 v69, v39, v136
	v_fmac_f32_e32 v84, v39, v128
	v_fmac_f32_e32 v85, v39, v120
	v_fmac_f32_e32 v95, v39, v112
	v_fmac_f32_e32 v20, v40, v159
	v_fmac_f32_e32 v41, v145, v40
	v_fmac_f32_e32 v69, v137, v40
	v_fmac_f32_e32 v84, v40, v129
	v_fmac_f32_e32 v85, v40, v121
	v_fmac_f32_e32 v95, v40, v113
	v_fmac_f32_e32 v20, v41, v138
	v_fmac_f32_e32 v69, v130, v41
	v_fmac_f32_e32 v84, v41, v122
	v_fmac_f32_e32 v85, v41, v114
	v_fmac_f32_e32 v95, v41, v106
	v_fmac_f32_e32 v20, v69, v139
	v_fmac_f32_e32 v84, v123, v69
	v_fmac_f32_e32 v85, v69, v115
	v_fmac_f32_e32 v95, v69, v107
	v_fmac_f32_e32 v20, v84, v140
	v_fmac_f32_e32 v85, v116, v84
	v_fmac_f32_e32 v95, v108, v84
	v_fmac_f32_e32 v20, v85, v141
	v_fmac_f32_e32 v95, v109, v85
	v_cmp_eq_u32_e32 vcc, 9, v174
	v_fmac_f32_e32 v20, v95, v78
	s_nop 0
	v_cndmask_b32_e64 v78, 0, 1.0, vcc
	v_fmac_f32_e32 v78, v21, v102
	v_fmac_f32_e32 v78, v29, v103
	v_fmac_f32_e32 v78, v39, v104
	v_fmac_f32_e32 v78, v40, v105
	v_fmac_f32_e32 v78, v41, v98
	v_fmac_f32_e32 v78, v69, v99
	v_fmac_f32_e32 v78, v84, v100
	v_fmac_f32_e32 v78, v101, v85
	v_fmac_f32_e32 v78, v94, v95
	v_cmp_eq_u32_e32 vcc, 10, v174
	v_fmac_f32_e32 v20, v78, v79
	s_nop 0
	v_cndmask_b32_e64 v79, 0, 1.0, vcc
	v_fmac_f32_e32 v79, v21, v90
	v_fmac_f32_e32 v79, v29, v91
	v_fmac_f32_e32 v79, v39, v92
	v_fmac_f32_e32 v79, v40, v93
	v_fmac_f32_e32 v79, v41, v86
	v_fmac_f32_e32 v79, v69, v87
	v_fmac_f32_e32 v79, v84, v88
	v_fmac_f32_e32 v79, v85, v89
	v_fmac_f32_e32 v79, v82, v95
	v_fmac_f32_e32 v79, v83, v78
	v_cmp_eq_u32_e32 vcc, 11, v174
	v_fmac_f32_e32 v20, v79, v80
	s_nop 0
	v_cndmask_b32_e64 v80, 0, 1.0, vcc
	v_fmac_f32_e32 v80, v21, v74
	v_fmac_f32_e32 v80, v29, v75
	v_fmac_f32_e32 v80, v39, v76
	v_fmac_f32_e32 v80, v40, v77
	v_fmac_f32_e32 v80, v41, v70
	v_fmac_f32_e32 v80, v69, v71
	v_fmac_f32_e32 v80, v84, v72
	v_fmac_f32_e32 v80, v85, v73
	v_cmp_eq_u32_e32 vcc, 12, v174
	v_fmac_f32_e32 v80, v95, v66
	v_fmac_f32_e32 v80, v67, v78
	v_cndmask_b32_e64 v66, 0, 1.0, vcc
	v_fmac_f32_e32 v66, v21, v62
	v_fmac_f32_e32 v66, v29, v63
	v_fmac_f32_e32 v66, v39, v64
	v_fmac_f32_e32 v66, v40, v65
	v_fmac_f32_e32 v66, v41, v58
	v_fmac_f32_e32 v66, v69, v59
	v_fmac_f32_e32 v66, v84, v60
	v_fmac_f32_e32 v66, v85, v61
	v_fmac_f32_e32 v66, v95, v54
	v_fmac_f32_e32 v66, v78, v55
	v_fmac_f32_e32 v80, v68, v79
	v_fmac_f32_e32 v66, v56, v79
	v_fmac_f32_e32 v20, v80, v81
	v_fmac_f32_e32 v66, v57, v80
	v_cmp_eq_u32_e32 vcc, 13, v174
	v_fmac_f32_e32 v20, v66, v26
	s_nop 0
	v_cndmask_b32_e64 v26, 0, 1.0, vcc
	v_fmac_f32_e32 v26, v21, v50
	v_fmac_f32_e32 v26, v29, v51
	v_fmac_f32_e32 v26, v39, v52
	v_fmac_f32_e32 v26, v40, v53
	v_fmac_f32_e32 v26, v41, v46
	v_fmac_f32_e32 v26, v69, v47
	v_fmac_f32_e32 v26, v84, v48
	v_fmac_f32_e32 v26, v85, v49
	v_fmac_f32_e32 v26, v95, v42
	v_fmac_f32_e32 v26, v78, v43
	v_fmac_f32_e32 v26, v79, v44
	v_fmac_f32_e32 v26, v45, v80
	v_fmac_f32_e32 v26, v38, v66
	v_cmp_eq_u32_e32 vcc, 14, v174
	v_fmac_f32_e32 v20, v27, v26
	s_nop 0
	v_cndmask_b32_e64 v27, 0, 1.0, vcc
	v_fmac_f32_e32 v27, v21, v34
	v_fmac_f32_e32 v27, v29, v35
	v_fmac_f32_e32 v27, v39, v36
	v_fmac_f32_e32 v27, v40, v37
	v_fmac_f32_e32 v27, v41, v30
	v_fmac_f32_e32 v27, v69, v31
	v_fmac_f32_e32 v27, v84, v32
	v_fmac_f32_e32 v27, v85, v33
	v_fmac_f32_e32 v27, v95, v22
	v_fmac_f32_e32 v27, v78, v23
	v_fmac_f32_e32 v27, v79, v24
	v_fmac_f32_e32 v27, v80, v25
	v_fmac_f32_e32 v27, v18, v66
	v_lshl_add_u32 v18, v174, 2, s31
	v_fmac_f32_e32 v27, v19, v26
	v_add_u32_e32 v19, 0x9400, v18
	v_add_u32_e32 v18, 0x9800, v18
	v_fmac_f32_e32 v20, v28, v27
	ds_write2_b32 v19, v21, v29 offset0:160 offset1:176
	ds_write2_b32 v19, v39, v40 offset0:192 offset1:208
	ds_write2_b32 v19, v41, v69 offset0:224 offset1:240
	ds_write2_b32 v18, v84, v85 offset1:16
	ds_write2_b32 v18, v95, v78 offset0:32 offset1:48
	ds_write2_b32 v18, v79, v80 offset0:64 offset1:80
	ds_write2_b32 v18, v66, v26 offset0:96 offset1:112
	ds_write2_b32 v18, v27, v20 offset0:128 offset1:144
.LBB0_936:
	s_or_b64 exec, exec, s[0:1]
	s_waitcnt lgkmcnt(0)
	s_waitcnt lgkmcnt(4)
	ds_read_b128 v[18:21], v242 offset:38528
	v_add_u32_e32 v32, 0x8240, v243
	v_add_u32_e32 v33, 0x8248, v243
	v_add_u32_e32 v34, 0x8280, v243
	v_add_u32_e32 v35, 0x8288, v243
	s_waitcnt lgkmcnt(0)
	s_nop 0
	s_nop 0
	s_nop 0
	s_nop 0
	s_nop 0
	s_nop 0
	s_nop 0
	v_cvt_pk_bf16_f32 v18, v18, v19
	s_nop 0
	s_nop 0
	s_nop 0
	v_cvt_pk_bf16_f32 v19, v20, v21
	v_add_u32_e32 v36, 0x82c0, v243
	v_add_u32_e32 v37, 0x82c8, v243
	v_add_u32_e32 v38, 0x8300, v243
	v_add_u32_e32 v39, 0x8308, v243
	global_store_dwordx2 v[234:235], v[18:19], off
	ds_write2_b32 v32, v212, v213 offset1:1
	ds_write2_b32 v33, v210, v211 offset1:1
	ds_write2_b32 v34, v220, v221 offset1:1
	ds_write2_b32 v35, v218, v219 offset1:1
	ds_write2_b32 v36, v228, v229 offset1:1
	ds_write2_b32 v37, v226, v227 offset1:1
	ds_write2_b32 v38, v232, v233 offset1:1
	ds_write2_b32 v39, v230, v231 offset1:1
	s_waitcnt lgkmcnt(0)
	v_add_u32_e32 v40, 0x8000, v246
	ds_read2_b32 v[18:19], v40 offset0:144 offset1:160
	ds_read2_b32 v[22:23], v40 offset0:209 offset1:225
	v_add_u32_e32 v41, 0x8400, v246
	s_mov_b64 s[0:1], 0x1000
	v_lshl_add_u64 v[20:21], v[160:161], 0, s[0:1]
	s_waitcnt lgkmcnt(1)
	s_nop 0
	s_nop 0
	ds_read2_b32 v[24:25], v41 offset0:18 offset1:34
	s_waitcnt lgkmcnt(1)
	s_nop 0
	s_nop 0
	ds_read2_b32 v[26:27], v41 offset0:83 offset1:99
	s_nop 0
	v_cvt_pk_bf16_f32 v28, v18, v22
	s_waitcnt lgkmcnt(1)
	s_nop 0
	s_nop 0
	s_waitcnt lgkmcnt(0)
	s_nop 0
	s_nop 0
	s_nop 0
	v_cvt_pk_bf16_f32 v29, v24, v26
	s_nop 0
	s_nop 0
	s_nop 0
	s_nop 0
	s_nop 0
	v_cvt_pk_bf16_f32 v18, v19, v23
	s_nop 0
	s_nop 0
	s_nop 0
	s_nop 0
	s_nop 0
	v_lshl_add_u64 v[30:31], v[20:21], 0, v[188:189]
	v_cvt_pk_bf16_f32 v19, v25, v27
	ds_read2_b32 v[22:23], v40 offset0:176 offset1:192
	v_lshl_add_u64 v[24:25], v[20:21], 0, v[196:197]
	v_add_u32_e32 v42, 0x8200, v246
	global_store_dwordx2 v[30:31], v[28:29], off
	global_store_dwordx2 v[24:25], v[18:19], off
	ds_read2_b32 v[18:19], v42 offset0:113 offset1:129
	s_waitcnt lgkmcnt(1)
	s_nop 0
	s_nop 0
	ds_read2_b32 v[24:25], v41 offset0:50 offset1:66
	s_nop 0
	s_waitcnt lgkmcnt(1)
	s_nop 0
	s_nop 0
	ds_read2_b32 v[26:27], v41 offset0:115 offset1:131
	v_cvt_pk_bf16_f32 v28, v22, v18
	s_waitcnt lgkmcnt(1)
	s_nop 0
	s_nop 0
	s_nop 0
	s_waitcnt lgkmcnt(0)
	s_nop 0
	s_nop 0
	v_cvt_pk_bf16_f32 v29, v24, v26
	s_nop 0
	s_nop 0
	s_nop 0
	s_nop 0
	s_nop 0
	v_cvt_pk_bf16_f32 v18, v23, v19
	s_nop 0
	s_nop 0
	s_nop 0
	s_nop 0
	s_nop 0
	v_lshl_add_u64 v[30:31], v[20:21], 0, v[198:199]
	v_cvt_pk_bf16_f32 v19, v25, v27
	v_lshl_add_u64 v[20:21], v[20:21], 0, v[200:201]
	global_store_dwordx2 v[30:31], v[28:29], off
	global_store_dwordx2 v[20:21], v[18:19], off
	s_waitcnt lgkmcnt(0)
	ds_write2_b32 v32, v164, v165 offset1:1
	ds_write2_b32 v33, v162, v163 offset1:1
	ds_write2_b32 v34, v168, v169 offset1:1
	ds_write2_b32 v35, v166, v167 offset1:1
	ds_write2_b32 v36, v216, v217 offset1:1
	ds_write2_b32 v37, v214, v215 offset1:1
	ds_write2_b32 v38, v224, v225 offset1:1
	ds_write2_b32 v39, v222, v223 offset1:1
	s_waitcnt lgkmcnt(0)
	ds_read2_b32 v[18:19], v40 offset0:144 offset1:160
	ds_read2_b32 v[22:23], v40 offset0:209 offset1:225
	s_mov_b64 s[0:1], 0x1800
	v_lshl_add_u64 v[20:21], v[160:161], 0, s[0:1]
	v_lshl_add_u64 v[30:31], v[20:21], 0, v[188:189]
	s_waitcnt lgkmcnt(1)
	s_nop 0
	s_nop 0
	ds_read2_b32 v[24:25], v41 offset0:18 offset1:34
	s_waitcnt lgkmcnt(1)
	s_nop 0
	s_nop 0
	ds_read2_b32 v[26:27], v41 offset0:83 offset1:99
	s_nop 0
	v_cvt_pk_bf16_f32 v28, v18, v22
	s_waitcnt lgkmcnt(1)
	s_nop 0
	s_nop 0
	s_waitcnt lgkmcnt(0)
	s_nop 0
	s_nop 0
	s_nop 0
	v_cvt_pk_bf16_f32 v29, v24, v26
	s_nop 0
	s_nop 0
	s_nop 0
	s_nop 0
	s_nop 0
	v_cvt_pk_bf16_f32 v18, v19, v23
	s_nop 0
	s_nop 0
	s_nop 0
	s_nop 0
	s_nop 0
	ds_read2_b32 v[22:23], v40 offset0:176 offset1:192
	v_cvt_pk_bf16_f32 v19, v25, v27
	v_lshl_add_u64 v[24:25], v[20:21], 0, v[196:197]
	global_store_dwordx2 v[30:31], v[28:29], off
	global_store_dwordx2 v[24:25], v[18:19], off
	ds_read2_b32 v[18:19], v42 offset0:113 offset1:129
	s_waitcnt lgkmcnt(1)
	s_nop 0
	s_nop 0
	ds_read2_b32 v[24:25], v41 offset0:50 offset1:66
	s_nop 0
	s_waitcnt lgkmcnt(1)
	s_nop 0
	s_nop 0
	ds_read2_b32 v[26:27], v41 offset0:115 offset1:131
	v_cvt_pk_bf16_f32 v28, v22, v18
	s_waitcnt lgkmcnt(1)
	s_nop 0
	s_nop 0
	s_nop 0
	s_waitcnt lgkmcnt(0)
	s_nop 0
	s_nop 0
	v_cvt_pk_bf16_f32 v29, v24, v26
	s_nop 0
	s_nop 0
	s_nop 0
	s_nop 0
	s_nop 0
	v_cvt_pk_bf16_f32 v18, v23, v19
	s_nop 0
	s_nop 0
	s_nop 0
	s_nop 0
	s_nop 0
	v_lshl_add_u64 v[30:31], v[20:21], 0, v[198:199]
	v_cvt_pk_bf16_f32 v19, v25, v27
	v_lshl_add_u64 v[20:21], v[20:21], 0, v[200:201]
	global_store_dwordx2 v[30:31], v[28:29], off
	global_store_dwordx2 v[20:21], v[18:19], off
	s_waitcnt lgkmcnt(0)
	s_and_b64 vcc, exec, s[14:15]
	s_mov_b64 s[0:1], -1
	s_cbranch_vccz .LBB0_930

.LBB0_1427:
	v_add_f32_e32 v34, v34, v35
	v_fmamk_f32 v34, v34, 0x3c000000, v108
	v_mul_f32_e32 v35, 0x4f800000, v34
	v_cmp_gt_f32_e32 vcc, s30, v34
	s_add_i32 s2, s2, s4
	s_add_i32 s25, s25, s22
	v_cndmask_b32_e32 v34, v34, v35, vcc
	v_sqrt_f32_e32 v35, v34
	s_add_i32 s3, s3, s23
	v_lshl_add_u64 v[76:77], v[76:77], 0, s[10:11]
	v_lshl_add_u64 v[72:73], v[72:73], 0, s[10:11]
	v_add_u32_e32 v36, -1, v35
	v_fma_f32 v38, -v36, v35, v34
	v_add_u32_e32 v37, 1, v35
	v_cmp_ge_f32_e64 s[0:1], 0, v38
	v_lshl_add_u64 v[78:79], v[78:79], 0, s[12:13]
	s_cmpk_lt_i32 s2, 0x4200
	v_cndmask_b32_e64 v36, v35, v36, s[0:1]
	v_fma_f32 v35, -v37, v35, v34
	v_cmp_lt_f32_e64 s[0:1], 0, v35
	v_lshl_add_u64 v[74:75], v[74:75], 0, s[10:11]
	s_nop 0
	v_cndmask_b32_e64 v35, v36, v37, s[0:1]
	v_mul_f32_e32 v36, 0x37800000, v35
	v_cndmask_b32_e32 v35, v35, v36, vcc
	v_cmp_class_f32_e32 vcc, v34, v63
	s_nop 1
	v_cndmask_b32_e32 v34, v35, v34, vcc
	v_div_scale_f32 v35, s[0:1], v34, v34, s36
	v_rcp_f32_e32 v36, v35
	s_nop 0
	v_fma_f32 v37, -v35, v36, 1.0
	v_fmac_f32_e32 v36, v37, v36
	v_div_scale_f32 v37, vcc, s36, v34, s36
	v_mul_f32_e32 v38, v37, v36
	v_fma_f32 v39, -v35, v38, v37
	v_fmac_f32_e32 v38, v39, v36
	v_fma_f32 v35, -v35, v38, v37
	v_div_fmas_f32 v35, v35, v36, v38
	v_div_fixup_f32 v34, v35, v34, s36
	v_mov_b32_e32 v37, v28
	v_mov_b32_e32 v28, v27
	v_pk_mul_f32 v[32:33], v[32:33], v[34:35] op_sel_hi:[1,0]
	v_mov_b32_e32 v36, v26
	v_pk_mul_f32 v[26:27], v[28:29], v[34:35] op_sel_hi:[1,0]
	v_pk_mul_f32 v[30:31], v[30:31], v[34:35] op_sel_hi:[1,0]
	v_pk_mul_f32 v[32:33], v[80:81], v[32:33]
	v_pk_mul_f32 v[36:37], v[36:37], v[34:35] op_sel_hi:[1,0]
	v_pk_mul_f32 v[26:27], v[4:5], v[26:27]
	v_pk_mul_f32 v[30:31], v[2:3], v[30:31]
	v_pk_mul_f32 v[36:37], v[6:7], v[36:37]
	s_nop 0
	s_nop 0
	s_nop 0
	s_nop 0
	s_nop 0
	s_nop 0
	s_nop 0
	s_nop 0
	s_nop 0
	s_nop 0
	s_nop 0
	s_nop 0
	s_nop 0
	s_nop 0
	s_nop 0
	s_nop 0
	s_nop 0
	s_nop 0
	s_nop 0
	s_nop 0
	v_cvt_pk_bf16_f32 v28, v36, v26
	v_cvt_pk_bf16_f32 v26, v30, v32
	v_add_co_u32_e32 v30, vcc, s34, v82
	v_cvt_pk_bf16_f32 v29, v37, v27
	v_cvt_pk_bf16_f32 v27, v31, v33
	v_addc_co_u32_e32 v31, vcc, 0, v83, vcc
	global_store_dwordx4 v[30:31], v[26:29], off offset:1024
	s_cbranch_scc0 .LBB0_1440

.LBB0_1436:
	s_waitcnt vmcnt(4)
	v_mov_b32_e32 v52, v39
	v_mov_b32_e32 v53, v40
	v_mov_b32_e32 v54, v38
	v_mov_b32_e32 v55, v41
	v_pk_add_f32 v[52:53], v[52:53], v[54:55]
	s_waitcnt vmcnt(2)
	v_mov_b32_e32 v54, v32
	v_mov_b32_e32 v55, v30
	v_mov_b32_e32 v56, v33
	v_mov_b32_e32 v57, v31
	v_pk_add_f32 v[54:55], v[54:55], v[56:57]
	v_add_f32_e32 v51, v52, v53
	v_add_f32_e32 v51, v51, v55
	v_add_f32_e32 v51, v54, v51
	s_cmpk_lt_i32 s2, 0x4000
	s_nop 0
	v_add_f32_dpp v51, v51, v51 quad_perm:[1,0,3,2] row_mask:0xf bank_mask:0xf bound_ctrl:1
	s_nop 1
	v_add_f32_dpp v51, v51, v51 quad_perm:[2,3,0,1] row_mask:0xf bank_mask:0xf bound_ctrl:1
	s_nop 1
	v_add_f32_dpp v51, v51, v51 row_half_mirror row_mask:0xf bank_mask:0xf bound_ctrl:1
	v_fmamk_f32 v39, v51, 0xbc800000, v39
	v_fmamk_f32 v38, v51, 0xbc800000, v38
	v_fmamk_f32 v41, v51, 0xbc800000, v41
	v_fmac_f32_e32 v40, 0xbc800000, v51
	v_pk_mul_f32 v[52:53], v[40:41], v[40:41]
	v_pk_mul_f32 v[54:55], v[38:39], v[38:39]
	v_fmamk_f32 v31, v51, 0xbc800000, v31
	v_fmamk_f32 v30, v51, 0xbc800000, v30
	v_fmamk_f32 v33, v51, 0xbc800000, v33
	v_fmac_f32_e32 v32, 0xbc800000, v51
	v_pk_mov_b32 v[56:57], v[54:55], v[52:53] op_sel:[1,0]
	v_mov_b32_e32 v55, v53
	v_pk_add_f32 v[52:53], v[56:57], v[54:55]
	v_pk_mul_f32 v[54:55], v[32:33], v[32:33]
	v_pk_mul_f32 v[56:57], v[30:31], v[30:31]
	v_mov_b32_e32 v82, v54
	v_mov_b32_e32 v83, v56
	v_mov_b32_e32 v56, v55
	v_pk_add_f32 v[54:55], v[82:83], v[56:57]
	v_add_f32_e32 v51, v52, v53
	v_add_f32_e32 v51, v55, v51
	v_add_f32_e32 v51, v54, v51
	v_lshl_add_u64 v[82:83], s[26:27], 0, v[72:73]
	s_nop 0
	v_add_f32_dpp v51, v51, v51 quad_perm:[1,0,3,2] row_mask:0xf bank_mask:0xf bound_ctrl:1
	s_nop 1
	v_add_f32_dpp v51, v51, v51 quad_perm:[2,3,0,1] row_mask:0xf bank_mask:0xf bound_ctrl:1
	s_nop 1
	v_add_f32_dpp v51, v51, v51 row_half_mirror row_mask:0xf bank_mask:0xf bound_ctrl:1
	v_fmamk_f32 v51, v51, 0x3c800000, v61
	v_mul_f32_e32 v52, 0x4f800000, v51
	v_cmp_gt_f32_e32 vcc, s30, v51
	s_nop 1
	v_cndmask_b32_e32 v51, v51, v52, vcc
	v_sqrt_f32_e32 v52, v51
	s_nop 0
	v_add_u32_e32 v53, -1, v52
	v_add_u32_e32 v54, 1, v52
	v_fma_f32 v55, -v53, v52, v51
	v_fma_f32 v56, -v54, v52, v51
	v_cmp_ge_f32_e64 s[0:1], 0, v55
	s_nop 1
	v_cndmask_b32_e64 v52, v52, v53, s[0:1]
	v_cmp_lt_f32_e64 s[0:1], 0, v56
	s_nop 1
	v_cndmask_b32_e64 v52, v52, v54, s[0:1]
	v_mul_f32_e32 v53, 0x37800000, v52
	v_cndmask_b32_e32 v52, v52, v53, vcc
	v_cmp_class_f32_e32 vcc, v51, v63
	s_nop 1
	v_cndmask_b32_e32 v51, v52, v51, vcc
	v_div_scale_f32 v52, s[0:1], v51, v51, 1.0
	v_rcp_f32_e32 v53, v52
	v_div_scale_f32 v54, vcc, 1.0, v51, 1.0
	s_mov_b64 s[0:1], -1
	v_fma_f32 v55, -v52, v53, 1.0
	v_fmac_f32_e32 v53, v55, v53
	v_mul_f32_e32 v55, v54, v53
	v_fma_f32 v56, -v52, v55, v54
	v_fmac_f32_e32 v55, v56, v53
	v_fma_f32 v52, -v52, v55, v54
	v_div_fmas_f32 v52, v52, v53, v55
	v_div_fixup_f32 v52, v52, v51, 1.0
	v_pk_mul_f32 v[38:39], v[38:39], v[52:53] op_sel_hi:[1,0]
	v_pk_mul_f32 v[30:31], v[30:31], v[52:53] op_sel_hi:[1,0]
	v_pk_fma_f32 v[38:39], v[14:15], v[38:39], v[22:23]
	v_pk_mul_f32 v[32:33], v[32:33], v[52:53] op_sel_hi:[1,0]
	s_waitcnt vmcnt(0)
	v_pk_fma_f32 v[38:39], v[46:47], v[172:173], v[38:39] op_sel_hi:[1,0,1]
	v_pk_fma_f32 v[32:33], v[12:13], v[32:33], v[20:21]
	v_pk_fma_f32 v[30:31], v[10:11], v[30:31], v[18:19]
	v_pk_mul_f32 v[40:41], v[40:41], v[52:53] op_sel_hi:[1,0]
	v_pk_mul_f32 v[34:35], v[34:35], v[38:39]
	v_pk_fma_f32 v[30:31], v[42:43], v[172:173], v[30:31] op_sel_hi:[1,0,1]
	v_pk_fma_f32 v[32:33], v[44:45], v[172:173], v[32:33] op_sel_hi:[1,0,1]
	v_pk_fma_f32 v[40:41], v[16:17], v[40:41], v[24:25]
	v_pk_mul_f32 v[32:33], v[28:29], v[32:33]
	v_pk_mul_f32 v[28:29], v[26:27], v[30:31]
	s_nop 0
	v_pk_fma_f32 v[40:41], v[48:49], v[172:173], v[40:41] op_sel_hi:[1,0,1]
	s_nop 0
	s_nop 0
	v_pk_mul_f32 v[36:37], v[36:37], v[40:41]
	s_nop 0
	s_nop 0
	v_cvt_pk_bf16_f32 v26, v34, v35
	s_nop 0
	s_nop 0
	s_nop 0
	s_nop 0
	s_nop 0
	v_cvt_pk_bf16_f32 v27, v36, v37
	s_nop 0
	s_nop 0
	s_nop 0
	s_nop 0
	s_nop 0
	v_cvt_pk_bf16_f32 v28, v28, v29
	s_nop 0
	s_nop 0
	s_nop 0
	s_nop 0
	s_nop 0
	v_cvt_pk_bf16_f32 v29, v32, v33
	v_add_co_u32_e32 v30, vcc, 0x30000000, v82
	s_nop 1
	v_addc_co_u32_e32 v31, vcc, 0, v83, vcc
	global_store_dwordx4 v[30:31], v[26:29], off
	s_cbranch_scc0 .LBB0_1438
	s_nop 0
	s_mov_b64 s[0:1], 0
	v_lshlrev_b32_e32 v34, 16, v176
	v_and_b32_e32 v35, 0xffff0000, v176
	v_lshlrev_b32_e32 v36, 16, v180
	v_and_b32_e32 v37, 0xffff0000, v180
	v_lshlrev_b32_e32 v26, 16, v177
	v_and_b32_e32 v27, 0xffff0000, v177
	v_lshlrev_b32_e32 v30, 16, v181
	v_and_b32_e32 v31, 0xffff0000, v181
	v_lshlrev_b32_e32 v38, 16, v178
	v_and_b32_e32 v39, 0xffff0000, v178
	v_lshlrev_b32_e32 v40, 16, v182
	v_and_b32_e32 v41, 0xffff0000, v182
	v_lshlrev_b32_e32 v28, 16, v179
	v_and_b32_e32 v29, 0xffff0000, v179
	v_lshlrev_b32_e32 v42, 16, v183
	v_and_b32_e32 v43, 0xffff0000, v183
	v_pk_fma_f32 v[36:37], v[70:71], v[36:37], v[34:35] neg_lo:[1,0,0] neg_hi:[1,0,0]
	v_pk_fma_f32 v[32:33], v[70:71], v[30:31], v[26:27] neg_lo:[1,0,0] neg_hi:[1,0,0]
	v_pk_fma_f32 v[26:27], v[70:71], v[40:41], v[38:39] neg_lo:[1,0,0] neg_hi:[1,0,0]
	v_pk_fma_f32 v[28:29], v[70:71], v[42:43], v[28:29] neg_lo:[1,0,0] neg_hi:[1,0,0]
	v_mov_b32_e32 v34, v36
	v_mov_b32_e32 v35, v32
	v_mov_b32_e32 v38, v37
	v_mov_b32_e32 v39, v33
	v_mov_b32_e32 v40, v28
	v_mov_b32_e32 v41, v26
	v_pk_mul_f32 v[34:35], v[34:35], v[34:35]
	v_mov_b32_e32 v42, v29
	v_mov_b32_e32 v43, v27
	v_pk_mul_f32 v[40:41], v[40:41], v[40:41]
	v_pk_fma_f32 v[34:35], v[38:39], v[38:39], v[34:35]
	v_mov_b32_e32 v31, v32
	v_pk_fma_f32 v[38:39], v[42:43], v[42:43], v[40:41]
	v_add_f32_e32 v32, v34, v35
	v_add_f32_e32 v32, v39, v32
	v_add_f32_e32 v32, v38, v32
	v_mov_b32_e32 v30, v36
	s_nop 0
	v_add_f32_dpp v32, v32, v32 quad_perm:[1,0,3,2] row_mask:0xf bank_mask:0xf bound_ctrl:1
	s_nop 1
	v_add_f32_dpp v32, v32, v32 quad_perm:[2,3,0,1] row_mask:0xf bank_mask:0xf bound_ctrl:1
	s_nop 1
	v_add_f32_dpp v34, v32, v32 row_half_mirror row_mask:0xf bank_mask:0xf bound_ctrl:1
	v_mov_b32_e32 v32, v37
	s_nop 0
	v_mov_b32_dpp v35, v34 row_mirror row_mask:0xf bank_mask:0xf bound_ctrl:1
